# inside the grid barrier waves 1-7 touch the weight matrix of the phase after next (LDS-DMA dword per 64 B into unused LDS), hidden under the barrier protocol
# baseline (speedup 1.0000x reference)
; __device__ __forceinline__ unsigned xb_ld(unsigned* p)              { return __hip_atomic_load(p, __ATOMIC_RELAXED, __HIP_MEMORY_SCOPE_AGENT); }
; __device__ __forceinline__ unsigned xb_add(unsigned* p, unsigned v) { return __hip_atomic_fetch_add(p, v, __ATOMIC_RELAXED, __HIP_MEMORY_SCOPE_AGENT); }
; #define XB_SPIN(cond, bar) do { unsigned _sp = 0; while (cond) { __builtin_amdgcn_s_sleep(1); \
;     if ((++_sp & 255u) == 0u) { if (xb_ld(&(bar)[XB_TMO])) break; if (_sp > XB_SPIN_CAP) { atomicAdd(&(bar)[XB_TMO], 1u); break; } } } } while (0)
; __device__ __forceinline__ void xcd_barrier(const XcdBarrier& b) {
;     asm volatile("s_waitcnt vmcnt(0)" ::: "memory");
;     __syncthreads();
;     if (threadIdx.x == 0) {
;         unsigned* bar = b.bar;
;         __builtin_amdgcn_s_waitcnt(0);
;         unsigned nloc = b.st[0], nx = b.st[1];
;         if (nloc == 0u) { xcd_barrier_complete(bar, b.x, nloc, nx); b.st[0] = nloc; b.st[1] = nx; }
;         const unsigned old = xb_add(&bar[XB_XSUB(b.x)], 1u);
;         const unsigned gen = old / nloc;
;         if (old + 1u == (gen + 1u) * nloc) {
;             __builtin_amdgcn_fence(__ATOMIC_RELEASE, "agent");
;             asm volatile("s_waitcnt vmcnt(0)" ::: "memory");
;             const unsigned og = xb_add(&bar[XB_TOP], 1u);
;             const unsigned tg = og / nx;
;             if (og + 1u == (tg + 1u) * nx) xb_add(&bar[XB_TOPGEN], 1u);
;             else XB_SPIN(xb_ld(&bar[XB_TOPGEN]) == tg, bar);
;             __builtin_amdgcn_fence(__ATOMIC_ACQUIRE, "agent");
;             xb_add(&bar[XB_XGEN(b.x)], 1u);
;             asm volatile("s_waitcnt vmcnt(0)" ::: "memory");
;         } else {
;             XB_SPIN(xb_ld(&bar[XB_XGEN(b.x)]) == gen, bar);
;             __builtin_amdgcn_fence(__ATOMIC_ACQUIRE, "agent");
;             asm volatile("s_waitcnt vmcnt(0)" ::: "memory");
;         }
;     }
;     __syncthreads();
; }
.LBB0_471:
	s_waitcnt vmcnt(0)
	s_waitcnt vmcnt(0)
	s_barrier
	v_readfirstlane_b32 s0, v196
	v_readlane_b32 s1, v254, 6
	s_nop 1
	s_lshr_b32 s0, s0, 6
	s_cmp_eq_u32 s0, 0
	s_cbranch_scc1 .Lwpf_skip
	s_cmp_gt_u32 s20, 70
	s_cbranch_scc1 .Lwpf_skip
	s_add_i32 s1, s1, s0
	s_add_i32 vcc_hi, s20, 1
	s_mul_hi_u32 s4, vcc_hi, 0x38e38e39
	s_lshr_b32 s4, s4, 2
	s_mul_i32 s4, s4, 18
	s_sub_u32 s4, vcc_hi, s4
	s_mul_hi_u32 s5, s4, 0x38e38e39
	s_lshr_b32 s5, s5, 1
	s_mul_i32 vcc_lo, s5, 9
	s_sub_u32 s4, s4, vcc_lo
	s_mov_b32 vcc_lo, 0
	s_mov_b32 vcc_hi, 0
	s_cmp_eq_u32 s4, 0
	s_cselect_b32 vcc_lo, 0xb00000, vcc_lo
	s_cselect_b32 vcc_hi, 0x0, vcc_hi
	s_cmp_eq_u32 s4, 1
	s_cselect_b32 vcc_lo, 0x580000, vcc_lo
	s_cselect_b32 vcc_hi, 0xb00000, vcc_hi
	s_cmp_eq_u32 s4, 2
	s_cselect_b32 vcc_lo, 0xb80000, vcc_lo
	s_cselect_b32 vcc_hi, 0x1080000, vcc_hi
	s_cmp_eq_u32 s4, 5
	s_cselect_b32 vcc_lo, 0x300000, vcc_lo
	s_cselect_b32 vcc_hi, 0x1c00000, vcc_hi
	s_cmp_eq_u32 s4, 6
	s_cselect_b32 vcc_lo, 0x200000, vcc_lo
	s_cselect_b32 vcc_hi, 0x1f00000, vcc_hi
	s_cmp_eq_u32 s4, 7
	s_cselect_b32 vcc_lo, 0xb00000, vcc_lo
	s_cselect_b32 vcc_hi, 0x2100000, vcc_hi
	s_cmp_eq_u32 s4, 8
	s_cselect_b32 vcc_lo, 0x580000, vcc_lo
	s_cselect_b32 vcc_hi, 0x2c00000, vcc_hi
	s_cmp_eq_u32 vcc_lo, 0
	s_cbranch_scc1 .Lwpf_skip
	s_mul_i32 s100, s5, 0x3180000
	s_mul_hi_u32 s101, s5, 0x3180000
	s_add_u32 s100, s80, s100
	s_addc_u32 s101, s81, s101
	v_mbcnt_lo_u32_b32 v1, -1, 0
	v_mbcnt_hi_u32_b32 v1, -1, v1
	v_lshl_add_u32 v1, s1, 6, v1
	v_lshlrev_b32_e32 v1, 6, v1
	s_add_i32 s4, vcc_lo, -64
	v_min_u32_e32 v0, s4, v1
	v_add_u32_e32 v0, vcc_hi, v0
	s_lshl_b32 s0, s0, 9
	s_add_i32 m0, s0, 0x20000
	s_nop 0
	global_load_lds_dword v0, s[100:101]
	v_add_u32_e32 v1, 0x800000, v1
	v_min_u32_e32 v0, s4, v1
	v_add_u32_e32 v0, vcc_hi, v0
	s_add_i32 m0, s0, 0x20100
	s_nop 0
	global_load_lds_dword v0, s[100:101]
	s_waitcnt vmcnt(0)
.Lwpf_skip:
	s_mov_b64 s[0:1], exec
	v_readlane_b32 s4, v253, 2
	v_readlane_b32 s5, v253, 3
	s_and_b64 s[4:5], s[0:1], s[4:5]
	s_mov_b64 exec, s[4:5]
	s_cbranch_execz .LBB0_17
	v_readlane_b32 s4, v254, 52
	s_waitcnt vmcnt(0) expcnt(0) lgkmcnt(0)
	s_nop 0
	v_mov_b32_e32 v0, s4
	ds_read_b32 v2, v0
	v_readlane_b32 s4, v254, 53
	s_waitcnt lgkmcnt(0)
	v_cmp_ne_u32_e32 vcc, 0, v2
	v_mov_b32_e32 v0, s4
	ds_read_b32 v0, v0
	s_cbranch_vccnz .LBB0_487
	s_mov_b32 s21, 1
	s_branch .LBB0_475
